# first pre-norm row phase: all scale/shift/gain fragment loads of a row issued up front (no per-block load-after-store waits)
# speedup vs baseline: 1.0295x; 1.0019x over previous
.LBB0_224:
	v_cmp_gt_i32_e64 s[6:7], s23, v12
	v_cmp_lt_i32_e32 vcc, s24, v12
	v_add_u32_e32 v16, 0xffffc000, v12
	s_and_saveexec_b64 s[2:3], vcc
	s_xor_b64 s[2:3], exec, s[2:3]
	v_lshlrev_b64 v[0:1], 12, v[16:17]
	v_lshl_add_u64 v[0:1], s[10:11], 0, v[0:1]
	v_mov_b32_e32 v13, v17
	s_andn2_saveexec_b64 s[2:3], s[2:3]
	v_ashrrev_i32_e32 v13, 31, v12
	v_lshlrev_b64 v[0:1], 12, v[12:13]
	v_lshl_add_u64 v[0:1], s[8:9], 0, v[0:1]
	s_or_b64 exec, exec, s[2:3]
	v_lshlrev_b32_e32 v40, 2, v14
	v_mov_b32_e32 v41, v17
	v_lshl_add_u64 v[38:39], v[0:1], 0, v[40:41]
	global_load_dwordx4 v[54:57], v[38:39], off nt
	global_load_dwordx4 v[8:11], v[38:39], off offset:1024 nt
	global_load_dwordx4 v[4:7], v[38:39], off offset:2048 nt
	global_load_dwordx4 v[0:3], v[38:39], off offset:3072 nt
	v_lshrrev_b32_e32 v35, 3, v16
	v_ashrrev_i32_e32 v33, 11, v12
	v_add_u32_e32 v35, 8, v35
	v_mov_b64_e32 v[38:39], s[16:17]
	v_cndmask_b32_e64 v33, v35, v33, s[6:7]
	v_mad_i64_i32 v[42:43], s[2:3], v33, s26, v[38:39]
	v_lshl_add_u64 v[38:39], v[42:43], 0, s[20:21]
	v_lshl_add_u64 v[48:49], v[38:39], 0, v[40:41]
	global_load_dwordx4 v[44:47], v[48:49], off
	global_load_dwordx4 v[58:61], v[22:23], off
	v_lshl_add_u64 v[40:41], v[42:43], 0, v[40:41]
	global_load_dwordx4 v[62:65], v[40:41], off
	v_mov_b32_e32 v117, 0
	global_load_dwordx4 v[120:123], v[22:23], off offset:1024
	v_mov_b32_e32 v116, v32
	v_lshl_add_u64 v[118:119], v[38:39], 0, v[116:117]
	global_load_dwordx4 v[124:127], v[118:119], off
	global_load_dwordx4 v[128:131], v[40:41], off offset:1024
	global_load_dwordx4 v[132:135], v[22:23], off offset:2048
	v_mov_b32_e32 v116, v34
	v_lshl_add_u64 v[118:119], v[38:39], 0, v[116:117]
	global_load_dwordx4 v[136:139], v[118:119], off
	global_load_dwordx4 v[140:143], v[40:41], off offset:2048
	global_load_dwordx4 v[144:147], v[22:23], off offset:3072
	v_mov_b32_e32 v116, v36
	v_lshl_add_u64 v[118:119], v[38:39], 0, v[116:117]
	global_load_dwordx4 v[148:151], v[118:119], off
	global_load_dwordx4 v[152:155], v[40:41], off offset:3072
	v_lshlrev_b32_e32 v37, 1, v16
	v_and_or_b32 v16, v16, 15, v18
	v_lshlrev_b32_e32 v16, 4, v16
	s_waitcnt vmcnt(15)
	v_mov_b32_e32 v48, v55
	s_waitcnt vmcnt(14)
	v_mov_b32_e32 v49, v9
	v_mov_b32_e32 v42, v54
	v_mov_b32_e32 v43, v8
	s_waitcnt vmcnt(13)
	v_mov_b32_e32 v70, v5
	s_waitcnt vmcnt(12)
	v_mov_b32_e32 v71, v1
	v_pk_mul_f32 v[48:49], v[48:49], v[48:49]
	v_mov_b32_e32 v52, v56
	v_mov_b32_e32 v53, v10
	v_mov_b32_e32 v68, v4
	v_mov_b32_e32 v69, v0
	v_pk_mul_f32 v[70:71], v[70:71], v[70:71]
	v_pk_fma_f32 v[42:43], v[42:43], v[42:43], v[48:49]
	v_mov_b32_e32 v66, v57
	v_mov_b32_e32 v67, v11
	v_mov_b32_e32 v72, v6
	v_mov_b32_e32 v73, v2
	v_pk_fma_f32 v[48:49], v[68:69], v[68:69], v[70:71]
	v_pk_fma_f32 v[42:43], v[52:53], v[52:53], v[42:43]
	v_mov_b32_e32 v74, v7
	v_mov_b32_e32 v75, v3
	v_pk_fma_f32 v[48:49], v[72:73], v[72:73], v[48:49]
	v_pk_fma_f32 v[42:43], v[66:67], v[66:67], v[42:43]
	v_pk_fma_f32 v[48:49], v[74:75], v[74:75], v[48:49]
	v_add_f32_e32 v33, v42, v43
	v_add_f32_e32 v33, v33, v48
	v_add_f32_e32 v33, v33, v49
	ds_bpermute_b32 v35, v19, v33
	v_lshl_add_u64 v[42:43], v[20:21], 0, v[16:17]
	s_waitcnt vmcnt(11)
	v_pk_add_f32 v[48:49], v[46:47], 1.0 op_sel_hi:[1,0]
	v_and_b32_e32 v52, 0xffffffe0, v37
	v_pk_add_f32 v[44:45], v[44:45], 1.0 op_sel_hi:[1,0]
	s_waitcnt lgkmcnt(0)
	v_add_f32_e32 v33, v33, v35
	ds_bpermute_b32 v35, v25, v33
	s_waitcnt lgkmcnt(0)
	v_add_f32_e32 v33, v33, v35
	ds_bpermute_b32 v35, v27, v33
	s_waitcnt lgkmcnt(0)
	v_add_f32_e32 v33, v33, v35
	ds_bpermute_b32 v35, v29, v33
	s_waitcnt lgkmcnt(0)
	v_add_f32_e32 v33, v33, v35
	ds_bpermute_b32 v35, v31, v33
	s_waitcnt lgkmcnt(0)
	v_add_f32_e32 v33, v33, v35
	ds_bpermute_b32 v35, v50, v33
	s_waitcnt lgkmcnt(0)
	v_add_f32_e32 v33, v33, v35
	v_fmamk_f32 v33, v33, 0x3a800000, v51
	v_mul_f32_e32 v35, 0x4b800000, v33
	v_cmp_gt_f32_e64 s[6:7], s25, v33
	s_nop 1
	v_cndmask_b32_e64 v33, v33, v35, s[6:7]
	v_rsq_f32_e32 v33, v33
	s_nop 0
	v_mul_f32_e32 v16, 0x45800000, v33
	v_cndmask_b32_e64 v46, v33, v16, s[6:7]
	v_pk_mul_f32 v[56:57], v[56:57], v[46:47] op_sel_hi:[1,0]
	v_pk_mul_f32 v[54:55], v[54:55], v[46:47] op_sel_hi:[1,0]
	s_waitcnt vmcnt(10)
	v_pk_mul_f32 v[56:57], v[60:61], v[56:57]
	v_pk_mul_f32 v[54:55], v[58:59], v[54:55]
	s_waitcnt vmcnt(9)
	v_pk_fma_f32 v[56:57], v[48:49], v[56:57], v[64:65]
	v_pk_fma_f32 v[44:45], v[44:45], v[54:55], v[62:63]
	s_nop 0
	v_cvt_pk_bf16_f32 v48, v44, v45
	v_cvt_pk_bf16_f32 v49, v56, v57
	s_and_saveexec_b64 s[2:3], vcc
	s_xor_b64 s[2:3], exec, s[2:3]
	s_cbranch_execz .LBB0_230
	v_or_b32_e32 v16, v52, v24
	v_lshlrev_b64 v[44:45], 10, v[16:17]
	v_lshl_add_u64 v[44:45], v[42:43], 0, v[44:45]
	global_store_dwordx2 v[44:45], v[48:49], off

.LBB0_232:
	s_or_b64 exec, exec, s[2:3]
	v_mov_b32_e32 v33, v17
	v_lshl_add_u64 v[48:49], v[38:39], 0, v[32:33]
	v_mov_b32_e32 v47, v46
	v_mov_b32_e32 v48, v46
	v_mov_b32_e32 v49, v46
	v_pk_mul_f32 v[8:9], v[8:9], v[46:47]
	v_pk_mul_f32 v[10:11], v[10:11], v[48:49]
	s_waitcnt vmcnt(1)
	v_pk_mul_f32 v[8:9], v[8:9], v[120:121]
	v_pk_add_f32 v[54:55], v[124:125], 1.0 op_sel_hi:[1,0]
	v_pk_mul_f32 v[10:11], v[10:11], v[122:123]
	v_pk_add_f32 v[48:49], v[126:127], 1.0 op_sel_hi:[1,0]
	v_pk_fma_f32 v[8:9], v[54:55], v[8:9], v[128:129]
	v_pk_fma_f32 v[10:11], v[48:49], v[10:11], v[130:131]
	v_cvt_pk_bf16_f32 v8, v8, v9
	s_nop 0
	v_cvt_pk_bf16_f32 v9, v10, v11
	s_and_saveexec_b64 s[2:3], vcc
	s_xor_b64 s[2:3], exec, s[2:3]
	s_cbranch_execz .LBB0_234
	v_or_b32_e32 v10, v52, v26
	v_mov_b32_e32 v11, v17
	v_lshlrev_b64 v[10:11], 10, v[10:11]
	v_lshl_add_u64 v[10:11], v[42:43], 0, v[10:11]
	global_store_dwordx2 v[10:11], v[8:9], off

.LBB0_236:
	s_or_b64 exec, exec, s[2:3]
	v_mov_b32_e32 v35, v17
	v_lshl_add_u64 v[48:49], v[38:39], 0, v[34:35]
	v_mov_b32_e32 v48, v46
	v_mov_b32_e32 v49, v46
	v_pk_mul_f32 v[4:5], v[4:5], v[46:47]
	v_pk_mul_f32 v[6:7], v[6:7], v[48:49]
	s_waitcnt vmcnt(2)
	v_pk_mul_f32 v[4:5], v[4:5], v[132:133]
	v_pk_mul_f32 v[6:7], v[6:7], v[134:135]
	v_pk_add_f32 v[10:11], v[136:137], 1.0 op_sel_hi:[1,0]
	v_pk_add_f32 v[8:9], v[138:139], 1.0 op_sel_hi:[1,0]
	v_pk_fma_f32 v[4:5], v[10:11], v[4:5], v[140:141]
	v_pk_fma_f32 v[6:7], v[8:9], v[6:7], v[142:143]
	v_cvt_pk_bf16_f32 v4, v4, v5
	s_nop 0
	v_cvt_pk_bf16_f32 v5, v6, v7
	s_and_saveexec_b64 s[2:3], vcc
	s_xor_b64 s[2:3], exec, s[2:3]
	s_cbranch_execz .LBB0_238
	v_or_b32_e32 v6, v52, v28
	v_mov_b32_e32 v7, v17
	v_lshlrev_b64 v[6:7], 10, v[6:7]
	v_lshl_add_u64 v[6:7], v[42:43], 0, v[6:7]
	global_store_dwordx2 v[6:7], v[4:5], off

.LBB0_240:
	s_or_b64 exec, exec, s[2:3]
	v_mov_b32_e32 v37, v17
	v_lshl_add_u64 v[38:39], v[38:39], 0, v[36:37]
	v_mov_b32_e32 v38, v46
	v_mov_b32_e32 v39, v46
	v_pk_mul_f32 v[0:1], v[0:1], v[46:47]
	v_pk_mul_f32 v[2:3], v[2:3], v[38:39]
	s_waitcnt vmcnt(3)
	v_pk_mul_f32 v[0:1], v[0:1], v[144:145]
	v_pk_mul_f32 v[2:3], v[2:3], v[146:147]
	v_pk_add_f32 v[6:7], v[148:149], 1.0 op_sel_hi:[1,0]
	v_pk_add_f32 v[4:5], v[150:151], 1.0 op_sel_hi:[1,0]
	v_pk_fma_f32 v[0:1], v[6:7], v[0:1], v[152:153]
	v_pk_fma_f32 v[2:3], v[4:5], v[2:3], v[154:155]
	v_cvt_pk_bf16_f32 v0, v0, v1
	s_nop 0
	v_cvt_pk_bf16_f32 v1, v2, v3
	s_and_saveexec_b64 s[2:3], vcc
	s_xor_b64 s[2:3], exec, s[2:3]
	s_cbranch_execz .LBB0_242
	v_or_b32_e32 v16, v52, v30
	v_lshlrev_b64 v[2:3], 10, v[16:17]
	v_lshl_add_u64 v[2:3], v[42:43], 0, v[2:3]
	global_store_dwordx2 v[2:3], v[0:1], off
